# v112 + GDN deferred output store: chunk output stores issued right after the next chunk's vmcnt(0) so the wait no longer covers fresh store acks
# speedup vs baseline: 1.0023x; 1.0017x over previous
; __device__ __forceinline__ int otid() { int t = threadIdx.x; asm volatile("" : "+v"(t)); return t; }
; __device__ __forceinline__ void gdn_item(const Params& p, int item, float* sm) {
;   const int b = item >> 5, h = (item >> 3) & 3, c0 = (item & 7) * 16;
;   const bf16_t* gp = (const bf16_t*)p.out;
;   const float* gg = (const float*)(p.ws + OFF_GG);
;   bf16_t* O = (bf16_t*)(p.ws + OFF_O);
;   constexpr int TC = 16;
;   constexpr int BUF = 2 * TC * 128 + TC * 16 + 2 * TC + TC * 16 + TC;
;   const int tid = otid(), lane = tid & 63, wave = tid >> 6;
;   const int sub = lane & 15, cw = wave * 4 + (lane >> 4);
;   const int ltt = tid >> 4, lseg = tid & 15;
;   float S[8];
; #pragma unroll
;   for (int i = 0; i < 8; i++) S[i] = 0.f;
;   const size_t rowb = (size_t)b * LP;
;   uint4 pq, pk; bf16_t pv; float pg = 0.f, pb = 0.f;
;     ...
;   __syncthreads();
;   GDN_LOAD(PADR)
;   GDN_STORE(0)
;   __syncthreads();
.Lgd_item:
	s_setprio 3
	v_readlane_b32 s14, v244, 27
	v_readlane_b32 s8, v247, 3
	v_readlane_b32 s9, v247, 4
	v_readlane_b32 s4, v247, 1
	v_readlane_b32 s5, v247, 2
	v_and_b32_e32 v136, 15, v2
	v_lshrrev_b32_e32 v137, 4, v2
	v_bfe_u32 v138, v2, 4, 2
	v_lshrrev_b32_e32 v139, 6, v2
	s_lshr_b32 s10, s14, 5
	s_bfe_u32 s11, s14, 0x20003
	s_and_b32 s12, s14, 7
	s_lshl_b32 s12, s12, 5
	s_mul_i32 s13, s10, 0x2080
	s_add_i32 s13, s13, 0x70
	s_add_u32 s6, s8, 0x19c8c000
	s_addc_u32 s7, s9, 0
	s_add_u32 s8, s8, 0x19d90000
	s_addc_u32 s9, s9, 0
	s_lshl_b32 s14, s10, 2
	s_add_i32 s14, s14, s11
	s_mul_i32 s14, s14, 0x80400
	s_add_u32 s10, s4, 0x71a0000
	s_addc_u32 s15, s5, 0
	s_add_u32 s10, s10, s14
	s_addc_u32 s11, s15, 0
	v_readfirstlane_b32 s100, v139
	v_lshlrev_b32_e32 v151, 9, v136
	v_lshl_add_u32 v151, v139, 7, v151
	v_lshl_add_u32 v151, v138, 4, v151
	v_lshlrev_b32_e32 v152, 11, v138
	v_lshl_add_u32 v152, v139, 7, v152
	v_lshl_add_u32 v152, v136, 2, v152
	v_lshlrev_b32_e32 v153, 6, v136
	v_lshl_add_u32 v153, v138, 4, v153
	v_lshlrev_b32_e32 v154, 4, v138
	v_and_b32_e32 v140, 63, v2
	v_lshlrev_b32_e32 v156, 4, v140
	v_add_u32_e32 v156, 0x8a00, v156
	s_mul_i32 s101, s100, 0xc00
	v_add_u32_e32 v155, s101, v156
	v_lshlrev_b32_e32 v157, 5, v2
	v_lshl_add_u32 v158, v136, 4, v137
	v_lshlrev_b32_e32 v158, 2, v158
	v_add_u32_e32 v158, 16384, v158
	v_lshlrev_b32_e32 v159, 2, v136
	v_lshlrev_b32_e32 v141, 2, v138
	v_add_u32_e32 v142, 0, v141
	v_cmp_le_u32_e32 vcc, v142, v136
	s_nop 1
	v_cndmask_b32_e64 v166, 0, 1.0, vcc
	v_add_u32_e32 v142, 1, v141
	v_cmp_le_u32_e32 vcc, v142, v136
	s_nop 1
	v_cndmask_b32_e64 v167, 0, 1.0, vcc
	v_add_u32_e32 v142, 2, v141
	v_cmp_le_u32_e32 vcc, v142, v136
	s_nop 1
	v_cndmask_b32_e64 v168, 0, 1.0, vcc
	v_add_u32_e32 v142, 3, v141
	v_cmp_le_u32_e32 vcc, v142, v136
	s_nop 1
	v_cndmask_b32_e64 v169, 0, 1.0, vcc
	v_readlane_b32 s101, v244, 27
	s_bfe_u32 s101, s101, 0x20003
	v_add_u32_e32 v142, s13, v137
	s_lshl_b32 s14, s101, 8
	v_lshl_add_u32 v143, v136, 4, s14
	s_movk_i32 s15, 0xc00
	v_mad_u32_u24 v118, v142, s15, v143
	s_add_i32 s14, s14, s12
	v_lshl_add_u32 v143, v136, 1, s14
	v_mad_u32_u24 v119, v142, s15, v143
	v_add_u32_e32 v119, 0x800, v119
	v_add_u32_e32 v142, s13, v136
	s_lshl_b32 s15, s101, 2
	v_lshl_add_u32 v140, v142, 5, s15
	v_add_u32_e32 v142, s13, v141
	v_lshl_add_u32 v57, v142, 11, v143
	v_add_u32_e32 v57, 0x400, v57
	v_add_u32_e32 v58, 0x1000, v57
	v_lshlrev_b32_e32 v59, 6, v136
	v_lshl_add_u32 v59, v138, 4, v59
	v_readlane_b32 s14, v244, 27
	s_lshr_b32 s14, s14, 3
	s_mul_i32 s12, s14, 0x80400
	v_readlane_b32 s14, v247, 3
	v_readlane_b32 s15, v247, 4
	s_add_u32 s14, s14, 0xac40000
	s_addc_u32 s15, s15, 0
	s_add_u32 s14, s14, s12
	s_addc_u32 s15, s15, 0
	v_mov_b32_e32 v12, 0
	v_mov_b32_e32 v13, 0
	v_mov_b32_e32 v14, 0
	v_mov_b32_e32 v15, 0
	v_mov_b32_e32 v16, 0
	v_mov_b32_e32 v17, 0
	v_mov_b32_e32 v18, 0
	v_mov_b32_e32 v19, 0
	s_barrier
	global_load_dwordx4 v[108:111], v118, s[4:5]
	global_load_dwordx4 v[112:115], v118, s[4:5] offset:1024
	global_load_ushort v116, v119, s[4:5]
	global_load_dword v117, v140, s[6:7]
	s_add_u32 s4, s4, 0xc000
	s_addc_u32 s5, s5, 0
	s_add_u32 s6, s6, 0x200
	s_addc_u32 s7, s7, 0
	global_load_dwordx4 v[88:91], v59, s[10:11]
	s_add_u32 s10, s10, 0x400
	s_addc_u32 s11, s11, 0
	global_load_dwordx4 v[92:95], v59, s[14:15]
	s_add_u32 s14, s14, 0x400
	s_addc_u32 s15, s15, 0
	v_mov_b32_e32 v148, v157
	v_mov_b32_e32 v149, v158
	v_mov_b32_e32 v150, v159
	s_waitcnt vmcnt(0)
	v_lshlrev_b32_e32 v120, 16, v108
	v_and_b32_e32 v121, 0xffff0000, v108
	v_lshlrev_b32_e32 v122, 16, v109
	v_and_b32_e32 v123, 0xffff0000, v109
	v_lshlrev_b32_e32 v124, 16, v110
	v_and_b32_e32 v125, 0xffff0000, v110
	v_lshlrev_b32_e32 v126, 16, v111
	v_and_b32_e32 v127, 0xffff0000, v111
	v_lshlrev_b32_e32 v128, 16, v112
	v_and_b32_e32 v129, 0xffff0000, v112
	v_lshlrev_b32_e32 v130, 16, v113
	v_and_b32_e32 v131, 0xffff0000, v113
	v_lshlrev_b32_e32 v132, 16, v114
	v_and_b32_e32 v133, 0xffff0000, v114
	v_lshlrev_b32_e32 v134, 16, v115
	v_and_b32_e32 v135, 0xffff0000, v115
	v_mov_b32_e32 v136, v117
	v_lshlrev_b32_e32 v137, 16, v116
	s_nop 0
	v_add_f32_dpp v136, v136, v136 row_shr:1 row_mask:0xf bank_mask:0xf bound_ctrl:1
	s_nop 1
	v_add_f32_dpp v136, v136, v136 row_shr:2 row_mask:0xf bank_mask:0xf bound_ctrl:1
	s_nop 1
	v_add_f32_dpp v136, v136, v136 row_shr:4 row_mask:0xf bank_mask:0xf bound_ctrl:1
	s_nop 1
	v_add_f32_dpp v136, v136, v136 row_shr:8 row_mask:0xf bank_mask:0xf bound_ctrl:1
	s_nop 0
	v_max_f32_e32 v136, 0xc2a00000, v136
	v_mul_f32_e32 v136, 0x3fb8aa3b, v136
	v_exp_f32_e32 v138, v136
	v_exp_f32_e64 v139, -v136
	s_nop 0
	v_mul_f32_e32 v136, 0x3db504f3, v138
	ds_write_b128 v148, v[120:123]
	ds_write_b128 v148, v[124:127] offset:16
	ds_write_b128 v148, v[128:131] offset:8192
	ds_write_b128 v148, v[132:135] offset:8208
	ds_write_b32 v149, v137
	ds_write_b32 v150, v139 offset:17408
	ds_write_b32 v150, v138 offset:17536
	ds_write_b32 v150, v136 offset:17472
	global_load_dwordx4 v[108:111], v118, s[4:5]
	global_load_dwordx4 v[112:115], v118, s[4:5] offset:1024
	global_load_ushort v116, v119, s[4:5]
	global_load_dword v117, v140, s[6:7]
	s_add_u32 s4, s4, 0xc000
	s_addc_u32 s5, s5, 0
	s_add_u32 s6, s6, 0x200
	s_addc_u32 s7, s7, 0
	s_mov_b32 s0, 0
	s_mov_b32 s1, 0
	s_mov_b32 s101, 0
	s_sub_u32 s8, s8, 0x8000
	s_subb_u32 s9, s9, 0
	s_waitcnt lgkmcnt(0)
	s_barrier
; __device__ __forceinline__ void gdn_item(const Params& p, int item, float* sm) {
;     ...
;   for (int ch = 0; ch < NCH; ch++) {
;     const int bi = ch & 1;
;     const int t0 = PADR + ch * TC;
;     if (ch + 1 < NCH) GDN_LOAD(t0 + TC)
;     {
;       const float* bq = sm + bi * BUF;
;       const float* bk = bq + TC * 128;
;       const float* bv = bq + 2 * TC * 128;
;       const float* bg = bv + TC * 16;
;       float* bo = sm + bi * BUF + 2 * TC * 128 + TC * 16 + 2 * TC;
;       float oreg[TC];
; #pragma unroll
;       for (int t = 0; t < TC; t++) {
;         const float4 k0 = *(const float4*)(bk + t * 128 + sub * 4);
;         const float4 k1 = *(const float4*)(bk + t * 128 + 64 + sub * 4);
;         const float4 q0 = *(const float4*)(bq + t * 128 + sub * 4);
;         const float4 q1 = *(const float4*)(bq + t * 128 + 64 + sub * 4);
;         const float v = bv[t * 16 + cw];
;         const float g = bg[t], be = bg[TC + t];
;         const float qk = bo[TC * 16 + t];
;         float pa = k0.x * S[0] + k0.y * S[1];
;         float pb2 = k0.z * S[2] + k0.w * S[3];
;         float qa = q0.x * S[0] + q0.y * S[1];
;         float qb2 = q0.z * S[2] + q0.w * S[3];
;         pa += k1.x * S[4] + k1.y * S[5];
;         pb2 += k1.z * S[6] + k1.w * S[7];
;         qa += q1.x * S[4] + q1.y * S[5];
;         qb2 += q1.z * S[6] + q1.w * S[7];
;         const float ks = dpp_sum16(pa + pb2);
;         const float qs = dpp_sum16(qa + qb2);
;         const float coef = be * (v - g * ks);
;         const float oo = g * qs + coef * qk;
;         S[0] = g * S[0] + coef * k0.x; S[1] = g * S[1] + coef * k0.y; S[2] = g * S[2] + coef * k0.z; S[3] = g * S[3] + coef * k0.w;
;         S[4] = g * S[4] + coef * k1.x; S[5] = g * S[5] + coef * k1.y; S[6] = g * S[6] + coef * k1.z; S[7] = g * S[7] + coef * k1.w;
;         oreg[t] = oo * 0.08838834764831845f;
;       }
;       if (sub == 0) {
; #pragma unroll
;         for (int t = 0; t < TC; t++) bo[t * 16 + cw] = oreg[t];
;       }
;     }
;     if (ch + 1 < NCH) GDN_STORE(bi ^ 1)
.Lgd_chunk:
	v_add_u32_e32 v141, s1, v151
	v_add_u32_e32 v142, s1, v152
	v_add_u32_e32 v143, s1, v153
	v_add_u32_e32 v144, s1, v154
	v_mov_b32_e32 v145, s1
	s_xor_b32 s2, s1, 0x4500
	s_and_b32 s12, s0, 1
	s_mul_i32 s12, s12, 0x3000
	v_add_u32_e32 v146, s12, v155
	v_add_u32_e32 v147, s12, v156
	ds_read_b128 v[20:23], v141 offset:8192
	ds_read_b128 v[28:31], v141 offset:0
	ds_read_b128 v[24:27], v141 offset:8256
	ds_read_b128 v[32:35], v141 offset:64
	v_add_u32_e32 v148, s2, v157
	v_add_u32_e32 v149, s2, v158
	v_add_u32_e32 v150, s2, v159
	s_waitcnt lgkmcnt(0)
	v_mfma_f32_16x16x4_f32 v[60:63], v20, v12, 0
	ds_read_b32 v36, v142 offset:8192
	v_mfma_f32_16x16x4_f32 v[64:67], v28, v12, 0
	ds_read_b32 v37, v142 offset:8704
	v_mfma_f32_16x16x4_f32 v[60:63], v21, v13, v[60:63]
	ds_read_b32 v38, v142 offset:9216
	v_mfma_f32_16x16x4_f32 v[64:67], v29, v13, v[64:67]
	ds_read_b32 v39, v142 offset:9728
	s_waitcnt vmcnt(0)
	s_cmp_eq_u32 s101, 0
	s_cbranch_scc1 .Lgd_nopend
	global_store_short v57, v104, s[8:9]
	global_store_short v57, v105, s[8:9] offset:2048
	global_store_short v58, v106, s[8:9]
	global_store_short v58, v107, s[8:9] offset:2048
.Lgd_nopend:
	v_lshlrev_b32_e32 v120, 16, v108
	v_and_b32_e32 v121, 0xffff0000, v108
	v_lshlrev_b32_e32 v122, 16, v109
	v_mfma_f32_16x16x4_f32 v[60:63], v22, v14, v[60:63]
	ds_read_b32 v40, v142 offset:8256
	v_and_b32_e32 v123, 0xffff0000, v109
	v_lshlrev_b32_e32 v124, 16, v110
	v_and_b32_e32 v125, 0xffff0000, v110
	v_mfma_f32_16x16x4_f32 v[64:67], v30, v14, v[64:67]
	ds_read_b32 v41, v142 offset:8768
	v_lshlrev_b32_e32 v126, 16, v111
	v_and_b32_e32 v127, 0xffff0000, v111
	v_lshlrev_b32_e32 v128, 16, v112
	v_and_b32_e32 v129, 0xffff0000, v112
	v_mfma_f32_16x16x4_f32 v[60:63], v23, v15, v[60:63]
	ds_read_b32 v42, v142 offset:9280
	v_lshlrev_b32_e32 v130, 16, v113
	v_and_b32_e32 v131, 0xffff0000, v113
	v_lshlrev_b32_e32 v132, 16, v114
	v_mfma_f32_16x16x4_f32 v[64:67], v31, v15, v[64:67]
	ds_read_b32 v43, v142 offset:9792
	v_and_b32_e32 v133, 0xffff0000, v114
	v_lshlrev_b32_e32 v134, 16, v115
	v_and_b32_e32 v135, 0xffff0000, v115
	v_mov_b32_e32 v136, v117
	v_mfma_f32_16x16x4_f32 v[60:63], v24, v16, v[60:63]
	ds_read_b128 v[44:47], v143 offset:16384
	v_lshlrev_b32_e32 v137, 16, v116
	s_nop 0
	v_add_f32_dpp v136, v136, v136 row_shr:1 row_mask:0xf bank_mask:0xf bound_ctrl:1
	v_mfma_f32_16x16x4_f32 v[64:67], v32, v16, v[64:67]
	ds_read_b128 v[48:51], v144 offset:17408
	s_nop 1
	v_add_f32_dpp v136, v136, v136 row_shr:2 row_mask:0xf bank_mask:0xf bound_ctrl:1
	s_nop 1
	v_add_f32_dpp v136, v136, v136 row_shr:4 row_mask:0xf bank_mask:0xf bound_ctrl:1
	v_mfma_f32_16x16x4_f32 v[60:63], v25, v17, v[60:63]
	ds_read_b128 v[52:55], v144 offset:17472
	s_nop 1
	v_add_f32_dpp v136, v136, v136 row_shr:8 row_mask:0xf bank_mask:0xf bound_ctrl:1
	s_nop 0
	v_mfma_f32_16x16x4_f32 v[64:67], v33, v17, v[64:67]
	ds_read_b32 v56, v145 offset:17596
	v_max_f32_e32 v136, 0xc2a00000, v136
	v_mul_f32_e32 v136, 0x3fb8aa3b, v136
	v_exp_f32_e32 v138, v136
	v_exp_f32_e64 v139, -v136
	v_mfma_f32_16x16x4_f32 v[60:63], v26, v18, v[60:63]
	s_nop 0
	v_mul_f32_e32 v136, 0x3db504f3, v138
	ds_write_b128 v148, v[120:123]
	v_mfma_f32_16x16x4_f32 v[64:67], v34, v18, v[64:67]
	ds_write_b128 v148, v[124:127] offset:16
	ds_write_b128 v148, v[128:131] offset:8192
	ds_write_b128 v148, v[132:135] offset:8208
	ds_write_b32 v149, v137
	v_mfma_f32_16x16x4_f32 v[60:63], v27, v19, v[60:63]
	ds_write_b32 v150, v139 offset:17408
	ds_write_b32 v150, v138 offset:17536
	ds_write_b32 v150, v136 offset:17472
	v_mfma_f32_16x16x4_f32 v[64:67], v35, v19, v[64:67]
	global_load_dwordx4 v[108:111], v118, s[4:5]
	global_load_dwordx4 v[112:115], v118, s[4:5] offset:1024
	global_load_ushort v116, v119, s[4:5]
	global_load_dword v117, v140, s[6:7]
	s_cmp_lt_u32 s0, 0x1fe
	s_cselect_b32 s12, 0xc000, 0
	s_cselect_b32 s101, 0x200, 0
	s_add_u32 s4, s4, s12
	s_addc_u32 s5, s5, 0
	s_add_u32 s6, s6, s101
	s_addc_u32 s7, s7, 0
	s_nop 3
	ds_write_b128 v146, v[60:63]
	ds_write_b128 v146, v[64:67] offset:1024
	s_waitcnt lgkmcnt(0)
	s_barrier
	ds_read_b128 v[72:75], v147 offset:0
	ds_read_b128 v[76:79], v147 offset:3072
	ds_read_b128 v[80:83], v147 offset:6144
	ds_read_b128 v[84:87], v147 offset:9216
	s_waitcnt lgkmcnt(0)
	v_add_f32_e32 v72, v72, v76
	v_add_f32_e32 v80, v80, v84
	v_add_f32_e32 v73, v73, v77
	v_add_f32_e32 v81, v81, v85
	v_add_f32_e32 v74, v74, v78
	v_add_f32_e32 v82, v82, v86
	v_add_f32_e32 v75, v75, v79
	v_add_f32_e32 v83, v83, v87
	v_add_f32_e32 v72, v72, v80
	v_add_f32_e32 v73, v73, v81
	v_add_f32_e32 v74, v74, v82
	v_add_f32_e32 v75, v75, v83
	v_fma_f32 v96, v44, v48, -v72
	v_fma_f32 v97, v45, v49, -v73
	v_fma_f32 v98, v46, v50, -v74
	v_fma_f32 v99, v47, v51, -v75
	s_nop 1
	v_mfma_f32_16x16x4_f32 v[100:103], v88, v96, 0
	v_mfma_f32_16x16x4_f32 v[100:103], v89, v97, v[100:103]
	v_mfma_f32_16x16x4_f32 v[100:103], v90, v98, v[100:103]
	v_mfma_f32_16x16x4_f32 v[100:103], v91, v99, v[100:103]
	global_load_dwordx4 v[88:91], v59, s[10:11]
	s_cmp_lt_u32 s0, 0x1ff
	s_cselect_b32 s12, 0x400, 0
	s_add_u32 s10, s10, s12
	s_addc_u32 s11, s11, 0
	s_and_b32 s12, s0, 3
	s_cmp_eq_u32 s12, s100
	s_cbranch_scc0 .Lgd_upd
	ds_read_b128 v[72:75], v147 offset:1024
	ds_read_b128 v[76:79], v147 offset:4096
	ds_read_b128 v[80:83], v147 offset:7168
	ds_read_b128 v[84:87], v147 offset:10240
	s_waitcnt lgkmcnt(0)
	v_add_f32_e32 v72, v72, v76
	v_add_f32_e32 v80, v80, v84
	v_add_f32_e32 v73, v73, v77
	v_add_f32_e32 v81, v81, v85
	v_add_f32_e32 v74, v74, v78
	v_add_f32_e32 v82, v82, v86
	v_add_f32_e32 v75, v75, v79
	v_add_f32_e32 v83, v83, v87
	v_add_f32_e32 v104, v72, v80
	v_add_f32_e32 v105, v73, v81
	v_add_f32_e32 v106, v74, v82
	v_add_f32_e32 v107, v75, v83
	s_nop 7
	s_nop 1
	v_mfma_f32_16x16x4_f32 v[104:107], v92, v100, v[104:107]
	v_mfma_f32_16x16x4_f32 v[104:107], v93, v101, v[104:107]
	v_mfma_f32_16x16x4_f32 v[104:107], v94, v102, v[104:107]
	v_mfma_f32_16x16x4_f32 v[104:107], v95, v103, v[104:107]
; __device__ __forceinline__ void gdn_item(const Params& p, int item, float* sm) {
;     ...
;         const float ks = dpp_sum16(pa + pb2);
;         const float qs = dpp_sum16(qa + qb2);
;         const float coef = be * (v - g * ks);
;         const float oo = g * qs + coef * qk;
;         S[0] = g * S[0] + coef * k0.x; S[1] = g * S[1] + coef * k0.y; S[2] = g * S[2] + coef * k0.z; S[3] = g * S[3] + coef * k0.w;
;         S[4] = g * S[4] + coef * k1.x; S[5] = g * S[5] + coef * k1.y; S[6] = g * S[6] + coef * k1.z; S[7] = g * S[7] + coef * k1.w;
;         oreg[t] = oo * 0.08838834764831845f;
;       }
;       if (sub == 0) {
; #pragma unroll
;         for (int t = 0; t < TC; t++) bo[t * 16 + cw] = oreg[t];
;       }
;     }
;     if (ch + 1 < NCH) GDN_STORE(bi ^ 1)
;     __syncthreads();
;     {
;       const float ov = sm[bi * BUF + 2 * TC * 128 + TC * 16 + 2 * TC + ltt * 16 + lseg];
;       O[(rowb + t0 + ltt) * D + 512 + h * 128 + c0 + lseg] = f2bf(ov);
;     }
.Lgd_upd:
	global_load_dwordx4 v[92:95], v59, s[14:15]
	s_cmp_lt_u32 s0, 0x1ff
	s_cselect_b32 s101, 0x400, 0
	s_add_u32 s14, s14, s101
	s_addc_u32 s15, s15, 0
	s_nop 5
	v_mfma_f32_16x16x4_f32 v[12:15], v36, v100, v[12:15]
	v_mfma_f32_16x16x4_f32 v[16:19], v40, v100, v[16:19]
	v_mfma_f32_16x16x4_f32 v[12:15], v37, v101, v[12:15]
	v_mfma_f32_16x16x4_f32 v[16:19], v41, v101, v[16:19]
	v_mfma_f32_16x16x4_f32 v[12:15], v38, v102, v[12:15]
	v_mfma_f32_16x16x4_f32 v[16:19], v42, v102, v[16:19]
	v_mfma_f32_16x16x4_f32 v[12:15], v39, v103, v[12:15]
	v_mfma_f32_16x16x4_f32 v[16:19], v43, v103, v[16:19]
	s_mov_b32 s101, 0
	s_cmp_eq_u32 s12, s100
	s_cbranch_scc0 .Lgd_noout
	s_nop 7
	s_nop 3
	v_mul_f32_e32 v104, v104, v52
	v_mul_f32_e32 v105, v105, v53
	v_mul_f32_e32 v106, v106, v54
	v_mul_f32_e32 v107, v107, v55
	v_cvt_pk_bf16_f32 v104, v104, v104
	v_cvt_pk_bf16_f32 v105, v105, v105
	v_cvt_pk_bf16_f32 v106, v106, v106
	v_cvt_pk_bf16_f32 v107, v107, v107
	s_mov_b32 s101, 1
.Lgd_noout:
	s_add_u32 s8, s8, 0x8000
	s_addc_u32 s9, s9, 0
	s_nop 6
	v_mul_f32_e32 v12, v12, v56
	v_mul_f32_e32 v13, v13, v56
	v_mul_f32_e32 v14, v14, v56
	v_mul_f32_e32 v15, v15, v56
	v_mul_f32_e32 v16, v16, v56
	v_mul_f32_e32 v17, v17, v56
	v_mul_f32_e32 v18, v18, v56
	v_mul_f32_e32 v19, v19, v56
	s_mov_b32 s1, s2
	s_add_i32 s0, s0, 1
	s_cmp_lg_u32 s0, 513
	s_cbranch_scc1 .Lgd_chunk
	s_cmp_eq_u32 s101, 0
	s_cbranch_scc1 .Lgd_nopend2
	global_store_short v57, v104, s[8:9]
	global_store_short v57, v105, s[8:9] offset:2048
	global_store_short v58, v106, s[8:9]
	global_store_short v58, v107, s[8:9] offset:2048
